# P6 epilogue parts 1 and 3 hand-written: 3 row blocks of x/ssqa loads in flight, y in place, DPP quad sums, direct stores
# speedup vs baseline: 1.0045x; 1.0016x over previous
.LBB0_532:
	s_nop 7
	v_lshrrev_b32_e32 v224, 2, v193
	v_and_b32_e32 v225, 3, v193
	v_lshl_add_u32 v224, v225, 4, v224
	v_lshlrev_b32_e32 v224, 2, v224
	ds_bpermute_b32 v0, v224, v0
	ds_bpermute_b32 v1, v224, v1
	ds_bpermute_b32 v2, v224, v2
	ds_bpermute_b32 v3, v224, v3
	ds_bpermute_b32 v4, v224, v4
	ds_bpermute_b32 v5, v224, v5
	ds_bpermute_b32 v6, v224, v6
	ds_bpermute_b32 v7, v224, v7
	ds_bpermute_b32 v8, v224, v8
	ds_bpermute_b32 v9, v224, v9
	ds_bpermute_b32 v10, v224, v10
	ds_bpermute_b32 v11, v224, v11
	ds_bpermute_b32 v12, v224, v12
	ds_bpermute_b32 v13, v224, v13
	ds_bpermute_b32 v14, v224, v14
	ds_bpermute_b32 v15, v224, v15
	ds_bpermute_b32 v16, v224, v16
	ds_bpermute_b32 v17, v224, v17
	ds_bpermute_b32 v18, v224, v18
	ds_bpermute_b32 v19, v224, v19
	ds_bpermute_b32 v20, v224, v20
	ds_bpermute_b32 v21, v224, v21
	ds_bpermute_b32 v22, v224, v22
	ds_bpermute_b32 v23, v224, v23
	ds_bpermute_b32 v24, v224, v24
	ds_bpermute_b32 v25, v224, v25
	ds_bpermute_b32 v26, v224, v26
	ds_bpermute_b32 v27, v224, v27
	ds_bpermute_b32 v28, v224, v28
	ds_bpermute_b32 v29, v224, v29
	ds_bpermute_b32 v30, v224, v30
	ds_bpermute_b32 v31, v224, v31
	ds_bpermute_b32 v32, v224, v32
	ds_bpermute_b32 v33, v224, v33
	ds_bpermute_b32 v34, v224, v34
	ds_bpermute_b32 v35, v224, v35
	ds_bpermute_b32 v36, v224, v36
	ds_bpermute_b32 v37, v224, v37
	ds_bpermute_b32 v38, v224, v38
	ds_bpermute_b32 v39, v224, v39
	ds_bpermute_b32 v40, v224, v40
	ds_bpermute_b32 v41, v224, v41
	ds_bpermute_b32 v42, v224, v42
	ds_bpermute_b32 v43, v224, v43
	ds_bpermute_b32 v44, v224, v44
	ds_bpermute_b32 v45, v224, v45
	ds_bpermute_b32 v46, v224, v46
	ds_bpermute_b32 v47, v224, v47
	ds_bpermute_b32 v48, v224, v48
	ds_bpermute_b32 v49, v224, v49
	ds_bpermute_b32 v50, v224, v50
	ds_bpermute_b32 v51, v224, v51
	ds_bpermute_b32 v52, v224, v52
	ds_bpermute_b32 v53, v224, v53
	ds_bpermute_b32 v54, v224, v54
	ds_bpermute_b32 v55, v224, v55
	ds_bpermute_b32 v56, v224, v56
	ds_bpermute_b32 v57, v224, v57
	ds_bpermute_b32 v58, v224, v58
	ds_bpermute_b32 v59, v224, v59
	ds_bpermute_b32 v60, v224, v60
	ds_bpermute_b32 v61, v224, v61
	ds_bpermute_b32 v62, v224, v62
	ds_bpermute_b32 v63, v224, v63
	ds_bpermute_b32 v64, v224, v64
	ds_bpermute_b32 v65, v224, v65
	ds_bpermute_b32 v66, v224, v66
	ds_bpermute_b32 v67, v224, v67
	ds_bpermute_b32 v68, v224, v68
	ds_bpermute_b32 v69, v224, v69
	ds_bpermute_b32 v70, v224, v70
	ds_bpermute_b32 v71, v224, v71
	ds_bpermute_b32 v72, v224, v72
	ds_bpermute_b32 v73, v224, v73
	ds_bpermute_b32 v74, v224, v74
	ds_bpermute_b32 v75, v224, v75
	ds_bpermute_b32 v76, v224, v76
	ds_bpermute_b32 v77, v224, v77
	ds_bpermute_b32 v78, v224, v78
	ds_bpermute_b32 v79, v224, v79
	ds_bpermute_b32 v80, v224, v80
	ds_bpermute_b32 v81, v224, v81
	ds_bpermute_b32 v82, v224, v82
	ds_bpermute_b32 v83, v224, v83
	ds_bpermute_b32 v84, v224, v84
	ds_bpermute_b32 v85, v224, v85
	ds_bpermute_b32 v86, v224, v86
	ds_bpermute_b32 v87, v224, v87
	ds_bpermute_b32 v88, v224, v88
	ds_bpermute_b32 v89, v224, v89
	ds_bpermute_b32 v90, v224, v90
	ds_bpermute_b32 v91, v224, v91
	ds_bpermute_b32 v92, v224, v92
	ds_bpermute_b32 v93, v224, v93
	ds_bpermute_b32 v94, v224, v94
	ds_bpermute_b32 v95, v224, v95
	ds_bpermute_b32 v112, v224, v112
	ds_bpermute_b32 v113, v224, v113
	ds_bpermute_b32 v114, v224, v114
	ds_bpermute_b32 v115, v224, v115
	ds_bpermute_b32 v116, v224, v116
	ds_bpermute_b32 v117, v224, v117
	ds_bpermute_b32 v118, v224, v118
	ds_bpermute_b32 v119, v224, v119
	ds_bpermute_b32 v120, v224, v120
	ds_bpermute_b32 v121, v224, v121
	ds_bpermute_b32 v122, v224, v122
	ds_bpermute_b32 v123, v224, v123
	ds_bpermute_b32 v124, v224, v124
	ds_bpermute_b32 v125, v224, v125
	ds_bpermute_b32 v126, v224, v126
	ds_bpermute_b32 v127, v224, v127
	ds_bpermute_b32 v128, v224, v128
	ds_bpermute_b32 v129, v224, v129
	ds_bpermute_b32 v130, v224, v130
	ds_bpermute_b32 v131, v224, v131
	ds_bpermute_b32 v132, v224, v132
	ds_bpermute_b32 v133, v224, v133
	ds_bpermute_b32 v134, v224, v134
	ds_bpermute_b32 v135, v224, v135
	ds_bpermute_b32 v136, v224, v136
	ds_bpermute_b32 v137, v224, v137
	ds_bpermute_b32 v138, v224, v138
	ds_bpermute_b32 v139, v224, v139
	ds_bpermute_b32 v140, v224, v140
	ds_bpermute_b32 v141, v224, v141
	ds_bpermute_b32 v142, v224, v142
	ds_bpermute_b32 v143, v224, v143
	s_waitcnt lgkmcnt(0)
	v_and_b32_e32 v175, 3, v193
	v_lshrrev_b32_e32 v96, 2, v193
	v_mov_b32_e32 v185, v193
	s_lshl_b32 s26, s67, 8
	v_add_u32_e32 v194, s49, v96
	v_add_u32_e32 v195, s26, v194
	v_lshl_add_u32 v156, v175, 2, s53
	v_lshlrev_b32_e32 v156, 2, v156
	v_mov_b32_e32 v157, 0
	s_lshr_b32 s84, s67, 6
	s_lshl_b32 s84, s84, 13
	s_add_u32 s84, s39, s84
	s_addc_u32 s85, s40, 0
	s_add_u32 s86, s10, 0x20000
	s_addc_u32 s87, s11, 0
	s_add_u32 s88, s10, 0x40000
	s_addc_u32 s89, s11, 0
	global_load_dwordx4 v[104:107], v156, s[84:85]
	global_load_dwordx4 v[100:103], v156, s[84:85] offset:64
	global_load_dwordx4 v[96:99], v156, s[84:85] offset:512
	global_load_dwordx4 v[108:111], v156, s[84:85] offset:576
	v_mov_b32_e32 v242, v195
	v_lshlrev_b32_e32 v243, 2, v242
	v_lshl_add_u32 v244, v242, 13, v156
	global_load_dword v228, v243, s[10:11]
	global_load_dword v229, v243, s[86:87]
	global_load_dword v230, v243, s[88:89]
	global_load_dwordx4 v[160:163], v244, s[64:65] nt
	global_load_dwordx4 v[164:167], v244, s[64:65] offset:64 nt
	global_load_dwordx4 v[168:171], v244, s[64:65] offset:512 nt
	global_load_dwordx4 v[172:175], v244, s[64:65] offset:576 nt
	v_add_u32_e32 v242, 16, v195
	v_lshlrev_b32_e32 v243, 2, v242
	v_lshl_add_u32 v244, v242, 13, v156
	global_load_dword v231, v243, s[10:11]
	global_load_dword v232, v243, s[86:87]
	global_load_dword v233, v243, s[88:89]
	global_load_dwordx4 v[196:199], v244, s[64:65] nt
	global_load_dwordx4 v[200:203], v244, s[64:65] offset:64 nt
	global_load_dwordx4 v[204:207], v244, s[64:65] offset:512 nt
	global_load_dwordx4 v[208:211], v244, s[64:65] offset:576 nt
	v_add_u32_e32 v242, 32, v195
	v_lshlrev_b32_e32 v243, 2, v242
	v_lshl_add_u32 v244, v242, 13, v156
	global_load_dword v234, v243, s[10:11]
	global_load_dword v235, v243, s[86:87]
	global_load_dword v236, v243, s[88:89]
	global_load_dwordx4 v[212:215], v244, s[64:65] nt
	global_load_dwordx4 v[216:219], v244, s[64:65] offset:64 nt
	global_load_dwordx4 v[220:223], v244, s[64:65] offset:512 nt
	global_load_dwordx4 v[224:227], v244, s[64:65] offset:576 nt
	s_waitcnt vmcnt(14)
	v_add_f32_e32 v238, v228, v229
	v_add_f32_e32 v238, v238, v230
	v_fmamk_f32 v238, v238, 0x3a2aaaab, v183
	v_rsq_f32_e32 v238, v238
	s_nop 0
	v_pk_mul_f32 v[140:141], v[140:141], v[238:239] op_sel_hi:[1,0]
	v_pk_mul_f32 v[142:143], v[142:143], v[238:239] op_sel_hi:[1,0]
	v_pk_fma_f32 v[140:141], v[104:105], v[140:141], v[160:161]
	v_pk_fma_f32 v[142:143], v[106:107], v[142:143], v[162:163]
	v_pk_mul_f32 v[136:137], v[136:137], v[238:239] op_sel_hi:[1,0]
	v_pk_mul_f32 v[138:139], v[138:139], v[238:239] op_sel_hi:[1,0]
	v_pk_fma_f32 v[136:137], v[100:101], v[136:137], v[164:165]
	v_pk_fma_f32 v[138:139], v[102:103], v[138:139], v[166:167]
	v_pk_mul_f32 v[132:133], v[132:133], v[238:239] op_sel_hi:[1,0]
	v_pk_mul_f32 v[134:135], v[134:135], v[238:239] op_sel_hi:[1,0]
	v_pk_fma_f32 v[132:133], v[96:97], v[132:133], v[168:169]
	v_pk_fma_f32 v[134:135], v[98:99], v[134:135], v[170:171]
	v_pk_mul_f32 v[128:129], v[128:129], v[238:239] op_sel_hi:[1,0]
	v_pk_mul_f32 v[130:131], v[130:131], v[238:239] op_sel_hi:[1,0]
	v_pk_fma_f32 v[128:129], v[108:109], v[128:129], v[172:173]
	v_pk_fma_f32 v[130:131], v[110:111], v[130:131], v[174:175]
	v_pk_mul_f32 v[240:241], v[140:141], v[140:141]
	v_pk_fma_f32 v[240:241], v[142:143], v[142:143], v[240:241]
	v_pk_fma_f32 v[240:241], v[136:137], v[136:137], v[240:241]
	v_pk_fma_f32 v[240:241], v[138:139], v[138:139], v[240:241]
	v_pk_fma_f32 v[240:241], v[132:133], v[132:133], v[240:241]
	v_pk_fma_f32 v[240:241], v[134:135], v[134:135], v[240:241]
	v_pk_fma_f32 v[240:241], v[128:129], v[128:129], v[240:241]
	v_pk_fma_f32 v[240:241], v[130:131], v[130:131], v[240:241]
	v_add_f32_e32 v240, v240, v241
	v_mov_b32_e32 v245, v194
	v_lshl_add_u32 v245, v245, 4, s51
	v_add_f32_dpp v240, v240, v240 quad_perm:[1,0,3,2] row_mask:0xf bank_mask:0xf
	s_nop 1
	v_add_f32_dpp v240, v240, v240 quad_perm:[2,3,0,1] row_mask:0xf bank_mask:0xf
	ds_write_b32 v245, v240
	v_add_u32_e32 v242, 48, v195
	v_lshlrev_b32_e32 v243, 2, v242
	v_lshl_add_u32 v244, v242, 13, v156
	global_load_dword v228, v243, s[10:11]
	global_load_dword v229, v243, s[86:87]
	global_load_dword v230, v243, s[88:89]
	global_load_dwordx4 v[160:163], v244, s[64:65] nt
	global_load_dwordx4 v[164:167], v244, s[64:65] offset:64 nt
	global_load_dwordx4 v[168:171], v244, s[64:65] offset:512 nt
	global_load_dwordx4 v[172:175], v244, s[64:65] offset:576 nt
	s_waitcnt vmcnt(14)
	v_add_f32_e32 v238, v231, v232
	v_add_f32_e32 v238, v238, v233
	v_fmamk_f32 v238, v238, 0x3a2aaaab, v183
	v_rsq_f32_e32 v238, v238
	s_nop 0
	v_pk_mul_f32 v[124:125], v[124:125], v[238:239] op_sel_hi:[1,0]
	v_pk_mul_f32 v[126:127], v[126:127], v[238:239] op_sel_hi:[1,0]
	v_pk_fma_f32 v[124:125], v[104:105], v[124:125], v[196:197]
	v_pk_fma_f32 v[126:127], v[106:107], v[126:127], v[198:199]
	v_pk_mul_f32 v[120:121], v[120:121], v[238:239] op_sel_hi:[1,0]
	v_pk_mul_f32 v[122:123], v[122:123], v[238:239] op_sel_hi:[1,0]
	v_pk_fma_f32 v[120:121], v[100:101], v[120:121], v[200:201]
	v_pk_fma_f32 v[122:123], v[102:103], v[122:123], v[202:203]
	v_pk_mul_f32 v[116:117], v[116:117], v[238:239] op_sel_hi:[1,0]
	v_pk_mul_f32 v[118:119], v[118:119], v[238:239] op_sel_hi:[1,0]
	v_pk_fma_f32 v[116:117], v[96:97], v[116:117], v[204:205]
	v_pk_fma_f32 v[118:119], v[98:99], v[118:119], v[206:207]
	v_pk_mul_f32 v[112:113], v[112:113], v[238:239] op_sel_hi:[1,0]
	v_pk_mul_f32 v[114:115], v[114:115], v[238:239] op_sel_hi:[1,0]
	v_pk_fma_f32 v[112:113], v[108:109], v[112:113], v[208:209]
	v_pk_fma_f32 v[114:115], v[110:111], v[114:115], v[210:211]
	v_pk_mul_f32 v[240:241], v[124:125], v[124:125]
	v_pk_fma_f32 v[240:241], v[126:127], v[126:127], v[240:241]
	v_pk_fma_f32 v[240:241], v[120:121], v[120:121], v[240:241]
	v_pk_fma_f32 v[240:241], v[122:123], v[122:123], v[240:241]
	v_pk_fma_f32 v[240:241], v[116:117], v[116:117], v[240:241]
	v_pk_fma_f32 v[240:241], v[118:119], v[118:119], v[240:241]
	v_pk_fma_f32 v[240:241], v[112:113], v[112:113], v[240:241]
	v_pk_fma_f32 v[240:241], v[114:115], v[114:115], v[240:241]
	v_add_f32_e32 v240, v240, v241
	v_add_u32_e32 v245, 16, v194
	v_lshl_add_u32 v245, v245, 4, s51
	v_add_f32_dpp v240, v240, v240 quad_perm:[1,0,3,2] row_mask:0xf bank_mask:0xf
	s_nop 1
	v_add_f32_dpp v240, v240, v240 quad_perm:[2,3,0,1] row_mask:0xf bank_mask:0xf
	ds_write_b32 v245, v240
	v_add_u32_e32 v242, 128, v195
	v_lshlrev_b32_e32 v243, 2, v242
	v_lshl_add_u32 v244, v242, 13, v156
	global_load_dword v231, v243, s[10:11]
	global_load_dword v232, v243, s[86:87]
	global_load_dword v233, v243, s[88:89]
	global_load_dwordx4 v[196:199], v244, s[64:65] nt
	global_load_dwordx4 v[200:203], v244, s[64:65] offset:64 nt
	global_load_dwordx4 v[204:207], v244, s[64:65] offset:512 nt
	global_load_dwordx4 v[208:211], v244, s[64:65] offset:576 nt
	s_waitcnt vmcnt(14)
	v_add_f32_e32 v238, v234, v235
	v_add_f32_e32 v238, v238, v236
	v_fmamk_f32 v238, v238, 0x3a2aaaab, v183
	v_rsq_f32_e32 v238, v238
	s_nop 0
	v_pk_mul_f32 v[92:93], v[92:93], v[238:239] op_sel_hi:[1,0]
	v_pk_mul_f32 v[94:95], v[94:95], v[238:239] op_sel_hi:[1,0]
	v_pk_fma_f32 v[92:93], v[104:105], v[92:93], v[212:213]
	v_pk_fma_f32 v[94:95], v[106:107], v[94:95], v[214:215]
	v_pk_mul_f32 v[88:89], v[88:89], v[238:239] op_sel_hi:[1,0]
	v_pk_mul_f32 v[90:91], v[90:91], v[238:239] op_sel_hi:[1,0]
	v_pk_fma_f32 v[88:89], v[100:101], v[88:89], v[216:217]
	v_pk_fma_f32 v[90:91], v[102:103], v[90:91], v[218:219]
	v_pk_mul_f32 v[84:85], v[84:85], v[238:239] op_sel_hi:[1,0]
	v_pk_mul_f32 v[86:87], v[86:87], v[238:239] op_sel_hi:[1,0]
	v_pk_fma_f32 v[84:85], v[96:97], v[84:85], v[220:221]
	v_pk_fma_f32 v[86:87], v[98:99], v[86:87], v[222:223]
	v_pk_mul_f32 v[80:81], v[80:81], v[238:239] op_sel_hi:[1,0]
	v_pk_mul_f32 v[82:83], v[82:83], v[238:239] op_sel_hi:[1,0]
	v_pk_fma_f32 v[80:81], v[108:109], v[80:81], v[224:225]
	v_pk_fma_f32 v[82:83], v[110:111], v[82:83], v[226:227]
	v_pk_mul_f32 v[240:241], v[92:93], v[92:93]
	v_pk_fma_f32 v[240:241], v[94:95], v[94:95], v[240:241]
	v_pk_fma_f32 v[240:241], v[88:89], v[88:89], v[240:241]
	v_pk_fma_f32 v[240:241], v[90:91], v[90:91], v[240:241]
	v_pk_fma_f32 v[240:241], v[84:85], v[84:85], v[240:241]
	v_pk_fma_f32 v[240:241], v[86:87], v[86:87], v[240:241]
	v_pk_fma_f32 v[240:241], v[80:81], v[80:81], v[240:241]
	v_pk_fma_f32 v[240:241], v[82:83], v[82:83], v[240:241]
	v_add_f32_e32 v240, v240, v241
	v_add_u32_e32 v245, 32, v194
	v_lshl_add_u32 v245, v245, 4, s51
	v_add_f32_dpp v240, v240, v240 quad_perm:[1,0,3,2] row_mask:0xf bank_mask:0xf
	s_nop 1
	v_add_f32_dpp v240, v240, v240 quad_perm:[2,3,0,1] row_mask:0xf bank_mask:0xf
	ds_write_b32 v245, v240
	v_add_u32_e32 v242, 144, v195
	v_lshlrev_b32_e32 v243, 2, v242
	v_lshl_add_u32 v244, v242, 13, v156
	global_load_dword v234, v243, s[10:11]
	global_load_dword v235, v243, s[86:87]
	global_load_dword v236, v243, s[88:89]
	global_load_dwordx4 v[212:215], v244, s[64:65] nt
	global_load_dwordx4 v[216:219], v244, s[64:65] offset:64 nt
	global_load_dwordx4 v[220:223], v244, s[64:65] offset:512 nt
	global_load_dwordx4 v[224:227], v244, s[64:65] offset:576 nt
	s_waitcnt vmcnt(14)
	v_add_f32_e32 v238, v228, v229
	v_add_f32_e32 v238, v238, v230
	v_fmamk_f32 v238, v238, 0x3a2aaaab, v183
	v_rsq_f32_e32 v238, v238
	s_nop 0
	v_pk_mul_f32 v[76:77], v[76:77], v[238:239] op_sel_hi:[1,0]
	v_pk_mul_f32 v[78:79], v[78:79], v[238:239] op_sel_hi:[1,0]
	v_pk_fma_f32 v[76:77], v[104:105], v[76:77], v[160:161]
	v_pk_fma_f32 v[78:79], v[106:107], v[78:79], v[162:163]
	v_pk_mul_f32 v[72:73], v[72:73], v[238:239] op_sel_hi:[1,0]
	v_pk_mul_f32 v[74:75], v[74:75], v[238:239] op_sel_hi:[1,0]
	v_pk_fma_f32 v[72:73], v[100:101], v[72:73], v[164:165]
	v_pk_fma_f32 v[74:75], v[102:103], v[74:75], v[166:167]
	v_pk_mul_f32 v[68:69], v[68:69], v[238:239] op_sel_hi:[1,0]
	v_pk_mul_f32 v[70:71], v[70:71], v[238:239] op_sel_hi:[1,0]
	v_pk_fma_f32 v[68:69], v[96:97], v[68:69], v[168:169]
	v_pk_fma_f32 v[70:71], v[98:99], v[70:71], v[170:171]
	v_pk_mul_f32 v[64:65], v[64:65], v[238:239] op_sel_hi:[1,0]
	v_pk_mul_f32 v[66:67], v[66:67], v[238:239] op_sel_hi:[1,0]
	v_pk_fma_f32 v[64:65], v[108:109], v[64:65], v[172:173]
	v_pk_fma_f32 v[66:67], v[110:111], v[66:67], v[174:175]
	v_pk_mul_f32 v[240:241], v[76:77], v[76:77]
	v_pk_fma_f32 v[240:241], v[78:79], v[78:79], v[240:241]
	v_pk_fma_f32 v[240:241], v[72:73], v[72:73], v[240:241]
	v_pk_fma_f32 v[240:241], v[74:75], v[74:75], v[240:241]
	v_pk_fma_f32 v[240:241], v[68:69], v[68:69], v[240:241]
	v_pk_fma_f32 v[240:241], v[70:71], v[70:71], v[240:241]
	v_pk_fma_f32 v[240:241], v[64:65], v[64:65], v[240:241]
	v_pk_fma_f32 v[240:241], v[66:67], v[66:67], v[240:241]
	v_add_f32_e32 v240, v240, v241
	v_add_u32_e32 v245, 48, v194
	v_lshl_add_u32 v245, v245, 4, s51
	v_add_f32_dpp v240, v240, v240 quad_perm:[1,0,3,2] row_mask:0xf bank_mask:0xf
	s_nop 1
	v_add_f32_dpp v240, v240, v240 quad_perm:[2,3,0,1] row_mask:0xf bank_mask:0xf
	ds_write_b32 v245, v240
	v_add_u32_e32 v242, 160, v195
	v_lshlrev_b32_e32 v243, 2, v242
	v_lshl_add_u32 v244, v242, 13, v156
	global_load_dword v228, v243, s[10:11]
	global_load_dword v229, v243, s[86:87]
	global_load_dword v230, v243, s[88:89]
	global_load_dwordx4 v[160:163], v244, s[64:65] nt
	global_load_dwordx4 v[164:167], v244, s[64:65] offset:64 nt
	global_load_dwordx4 v[168:171], v244, s[64:65] offset:512 nt
	global_load_dwordx4 v[172:175], v244, s[64:65] offset:576 nt
	s_waitcnt vmcnt(14)
	v_add_f32_e32 v238, v231, v232
	v_add_f32_e32 v238, v238, v233
	v_fmamk_f32 v238, v238, 0x3a2aaaab, v183
	v_rsq_f32_e32 v238, v238
	s_nop 0
	v_pk_mul_f32 v[60:61], v[60:61], v[238:239] op_sel_hi:[1,0]
	v_pk_mul_f32 v[62:63], v[62:63], v[238:239] op_sel_hi:[1,0]
	v_pk_fma_f32 v[60:61], v[104:105], v[60:61], v[196:197]
	v_pk_fma_f32 v[62:63], v[106:107], v[62:63], v[198:199]
	v_pk_mul_f32 v[56:57], v[56:57], v[238:239] op_sel_hi:[1,0]
	v_pk_mul_f32 v[58:59], v[58:59], v[238:239] op_sel_hi:[1,0]
	v_pk_fma_f32 v[56:57], v[100:101], v[56:57], v[200:201]
	v_pk_fma_f32 v[58:59], v[102:103], v[58:59], v[202:203]
	v_pk_mul_f32 v[52:53], v[52:53], v[238:239] op_sel_hi:[1,0]
	v_pk_mul_f32 v[54:55], v[54:55], v[238:239] op_sel_hi:[1,0]
	v_pk_fma_f32 v[52:53], v[96:97], v[52:53], v[204:205]
	v_pk_fma_f32 v[54:55], v[98:99], v[54:55], v[206:207]
	v_pk_mul_f32 v[48:49], v[48:49], v[238:239] op_sel_hi:[1,0]
	v_pk_mul_f32 v[50:51], v[50:51], v[238:239] op_sel_hi:[1,0]
	v_pk_fma_f32 v[48:49], v[108:109], v[48:49], v[208:209]
	v_pk_fma_f32 v[50:51], v[110:111], v[50:51], v[210:211]
	v_pk_mul_f32 v[240:241], v[60:61], v[60:61]
	v_pk_fma_f32 v[240:241], v[62:63], v[62:63], v[240:241]
	v_pk_fma_f32 v[240:241], v[56:57], v[56:57], v[240:241]
	v_pk_fma_f32 v[240:241], v[58:59], v[58:59], v[240:241]
	v_pk_fma_f32 v[240:241], v[52:53], v[52:53], v[240:241]
	v_pk_fma_f32 v[240:241], v[54:55], v[54:55], v[240:241]
	v_pk_fma_f32 v[240:241], v[48:49], v[48:49], v[240:241]
	v_pk_fma_f32 v[240:241], v[50:51], v[50:51], v[240:241]
	v_add_f32_e32 v240, v240, v241
	v_add_u32_e32 v245, 128, v194
	v_lshl_add_u32 v245, v245, 4, s51
	v_add_f32_dpp v240, v240, v240 quad_perm:[1,0,3,2] row_mask:0xf bank_mask:0xf
	s_nop 1
	v_add_f32_dpp v240, v240, v240 quad_perm:[2,3,0,1] row_mask:0xf bank_mask:0xf
	ds_write_b32 v245, v240
	v_add_u32_e32 v242, 176, v195
	v_lshlrev_b32_e32 v243, 2, v242
	v_lshl_add_u32 v244, v242, 13, v156
	global_load_dword v231, v243, s[10:11]
	global_load_dword v232, v243, s[86:87]
	global_load_dword v233, v243, s[88:89]
	global_load_dwordx4 v[196:199], v244, s[64:65] nt
	global_load_dwordx4 v[200:203], v244, s[64:65] offset:64 nt
	global_load_dwordx4 v[204:207], v244, s[64:65] offset:512 nt
	global_load_dwordx4 v[208:211], v244, s[64:65] offset:576 nt
	s_waitcnt vmcnt(14)
	v_add_f32_e32 v238, v234, v235
	v_add_f32_e32 v238, v238, v236
	v_fmamk_f32 v238, v238, 0x3a2aaaab, v183
	v_rsq_f32_e32 v238, v238
	s_nop 0
	v_pk_mul_f32 v[44:45], v[44:45], v[238:239] op_sel_hi:[1,0]
	v_pk_mul_f32 v[46:47], v[46:47], v[238:239] op_sel_hi:[1,0]
	v_pk_fma_f32 v[44:45], v[104:105], v[44:45], v[212:213]
	v_pk_fma_f32 v[46:47], v[106:107], v[46:47], v[214:215]
	v_pk_mul_f32 v[40:41], v[40:41], v[238:239] op_sel_hi:[1,0]
	v_pk_mul_f32 v[42:43], v[42:43], v[238:239] op_sel_hi:[1,0]
	v_pk_fma_f32 v[40:41], v[100:101], v[40:41], v[216:217]
	v_pk_fma_f32 v[42:43], v[102:103], v[42:43], v[218:219]
	v_pk_mul_f32 v[36:37], v[36:37], v[238:239] op_sel_hi:[1,0]
	v_pk_mul_f32 v[38:39], v[38:39], v[238:239] op_sel_hi:[1,0]
	v_pk_fma_f32 v[36:37], v[96:97], v[36:37], v[220:221]
	v_pk_fma_f32 v[38:39], v[98:99], v[38:39], v[222:223]
	v_pk_mul_f32 v[32:33], v[32:33], v[238:239] op_sel_hi:[1,0]
	v_pk_mul_f32 v[34:35], v[34:35], v[238:239] op_sel_hi:[1,0]
	v_pk_fma_f32 v[32:33], v[108:109], v[32:33], v[224:225]
	v_pk_fma_f32 v[34:35], v[110:111], v[34:35], v[226:227]
	v_pk_mul_f32 v[240:241], v[44:45], v[44:45]
	v_pk_fma_f32 v[240:241], v[46:47], v[46:47], v[240:241]
	v_pk_fma_f32 v[240:241], v[40:41], v[40:41], v[240:241]
	v_pk_fma_f32 v[240:241], v[42:43], v[42:43], v[240:241]
	v_pk_fma_f32 v[240:241], v[36:37], v[36:37], v[240:241]
	v_pk_fma_f32 v[240:241], v[38:39], v[38:39], v[240:241]
	v_pk_fma_f32 v[240:241], v[32:33], v[32:33], v[240:241]
	v_pk_fma_f32 v[240:241], v[34:35], v[34:35], v[240:241]
	v_add_f32_e32 v240, v240, v241
	v_add_u32_e32 v245, 144, v194
	v_lshl_add_u32 v245, v245, 4, s51
	v_add_f32_dpp v240, v240, v240 quad_perm:[1,0,3,2] row_mask:0xf bank_mask:0xf
	s_nop 1
	v_add_f32_dpp v240, v240, v240 quad_perm:[2,3,0,1] row_mask:0xf bank_mask:0xf
	ds_write_b32 v245, v240
	global_load_dwordx4 v[212:215], v156, s[58:59]
	global_load_dwordx4 v[216:219], v156, s[58:59] offset:64
	global_load_dwordx4 v[220:223], v156, s[58:59] offset:512
	global_load_dwordx4 v[224:227], v156, s[58:59] offset:576
	s_waitcnt vmcnt(11)
	v_add_f32_e32 v238, v228, v229
	v_add_f32_e32 v238, v238, v230
	v_fmamk_f32 v238, v238, 0x3a2aaaab, v183
	v_rsq_f32_e32 v238, v238
	s_nop 0
	v_pk_mul_f32 v[28:29], v[28:29], v[238:239] op_sel_hi:[1,0]
	v_pk_mul_f32 v[30:31], v[30:31], v[238:239] op_sel_hi:[1,0]
	v_pk_fma_f32 v[28:29], v[104:105], v[28:29], v[160:161]
	v_pk_fma_f32 v[30:31], v[106:107], v[30:31], v[162:163]
	v_pk_mul_f32 v[24:25], v[24:25], v[238:239] op_sel_hi:[1,0]
	v_pk_mul_f32 v[26:27], v[26:27], v[238:239] op_sel_hi:[1,0]
	v_pk_fma_f32 v[24:25], v[100:101], v[24:25], v[164:165]
	v_pk_fma_f32 v[26:27], v[102:103], v[26:27], v[166:167]
	v_pk_mul_f32 v[20:21], v[20:21], v[238:239] op_sel_hi:[1,0]
	v_pk_mul_f32 v[22:23], v[22:23], v[238:239] op_sel_hi:[1,0]
	v_pk_fma_f32 v[20:21], v[96:97], v[20:21], v[168:169]
	v_pk_fma_f32 v[22:23], v[98:99], v[22:23], v[170:171]
	v_pk_mul_f32 v[16:17], v[16:17], v[238:239] op_sel_hi:[1,0]
	v_pk_mul_f32 v[18:19], v[18:19], v[238:239] op_sel_hi:[1,0]
	v_pk_fma_f32 v[16:17], v[108:109], v[16:17], v[172:173]
	v_pk_fma_f32 v[18:19], v[110:111], v[18:19], v[174:175]
	v_pk_mul_f32 v[240:241], v[28:29], v[28:29]
	v_pk_fma_f32 v[240:241], v[30:31], v[30:31], v[240:241]
	v_pk_fma_f32 v[240:241], v[24:25], v[24:25], v[240:241]
	v_pk_fma_f32 v[240:241], v[26:27], v[26:27], v[240:241]
	v_pk_fma_f32 v[240:241], v[20:21], v[20:21], v[240:241]
	v_pk_fma_f32 v[240:241], v[22:23], v[22:23], v[240:241]
	v_pk_fma_f32 v[240:241], v[16:17], v[16:17], v[240:241]
	v_pk_fma_f32 v[240:241], v[18:19], v[18:19], v[240:241]
	v_add_f32_e32 v240, v240, v241
	v_add_u32_e32 v245, 160, v194
	v_lshl_add_u32 v245, v245, 4, s51
	v_add_f32_dpp v240, v240, v240 quad_perm:[1,0,3,2] row_mask:0xf bank_mask:0xf
	s_nop 1
	v_add_f32_dpp v240, v240, v240 quad_perm:[2,3,0,1] row_mask:0xf bank_mask:0xf
	ds_write_b32 v245, v240
	s_waitcnt vmcnt(4)
	v_add_f32_e32 v238, v231, v232
	v_add_f32_e32 v238, v238, v233
	v_fmamk_f32 v238, v238, 0x3a2aaaab, v183
	v_rsq_f32_e32 v238, v238
	s_nop 0
	v_pk_mul_f32 v[12:13], v[12:13], v[238:239] op_sel_hi:[1,0]
	v_pk_mul_f32 v[14:15], v[14:15], v[238:239] op_sel_hi:[1,0]
	v_pk_fma_f32 v[12:13], v[104:105], v[12:13], v[196:197]
	v_pk_fma_f32 v[14:15], v[106:107], v[14:15], v[198:199]
	v_pk_mul_f32 v[8:9], v[8:9], v[238:239] op_sel_hi:[1,0]
	v_pk_mul_f32 v[10:11], v[10:11], v[238:239] op_sel_hi:[1,0]
	v_pk_fma_f32 v[8:9], v[100:101], v[8:9], v[200:201]
	v_pk_fma_f32 v[10:11], v[102:103], v[10:11], v[202:203]
	v_pk_mul_f32 v[4:5], v[4:5], v[238:239] op_sel_hi:[1,0]
	v_pk_mul_f32 v[6:7], v[6:7], v[238:239] op_sel_hi:[1,0]
	v_pk_fma_f32 v[4:5], v[96:97], v[4:5], v[204:205]
	v_pk_fma_f32 v[6:7], v[98:99], v[6:7], v[206:207]
	v_pk_mul_f32 v[0:1], v[0:1], v[238:239] op_sel_hi:[1,0]
	v_pk_mul_f32 v[2:3], v[2:3], v[238:239] op_sel_hi:[1,0]
	v_pk_fma_f32 v[0:1], v[108:109], v[0:1], v[208:209]
	v_pk_fma_f32 v[2:3], v[110:111], v[2:3], v[210:211]
	v_pk_mul_f32 v[240:241], v[12:13], v[12:13]
	v_pk_fma_f32 v[240:241], v[14:15], v[14:15], v[240:241]
	v_pk_fma_f32 v[240:241], v[8:9], v[8:9], v[240:241]
	v_pk_fma_f32 v[240:241], v[10:11], v[10:11], v[240:241]
	v_pk_fma_f32 v[240:241], v[4:5], v[4:5], v[240:241]
	v_pk_fma_f32 v[240:241], v[6:7], v[6:7], v[240:241]
	v_pk_fma_f32 v[240:241], v[0:1], v[0:1], v[240:241]
	v_pk_fma_f32 v[240:241], v[2:3], v[2:3], v[240:241]
	v_add_f32_e32 v240, v240, v241
	v_add_u32_e32 v245, 176, v194
	v_lshl_add_u32 v245, v245, 4, s51
	v_add_f32_dpp v240, v240, v240 quad_perm:[1,0,3,2] row_mask:0xf bank_mask:0xf
	s_nop 1
	v_add_f32_dpp v240, v240, v240 quad_perm:[2,3,0,1] row_mask:0xf bank_mask:0xf
	ds_write_b32 v245, v240
	s_waitcnt lgkmcnt(0)
	s_barrier
	v_add_u32_e32 v98, s52, v185
	v_cndmask_b32_e64 v96, 0, 1, s[18:19]
	v_cmp_ne_u32_e64 s[2:3], 1, v96
	v_add_u32_e32 v96, s26, v98
	s_andn2_b64 vcc, exec, s[18:19]
	s_waitcnt lgkmcnt(0)
	v_ashrrev_i32_e32 v97, 31, v96
	s_cbranch_vccnz .LBB0_553
	v_lshl_add_u32 v99, v98, 4, 0
	v_add_u32_e32 v99, 0x20000, v99
	ds_read_b128 v[100:103], v99
	v_lshlrev_b64 v[104:105], 5, v[96:97]
	v_cmp_eq_u32_e32 vcc, 0, v185
	s_waitcnt lgkmcnt(0)
	v_mov_b32_e32 v106, v101
	v_mov_b32_e32 v107, v102
	v_mov_b32_e32 v101, v103
	v_pk_add_f32 v[100:101], v[106:107], v[100:101]
	v_lshl_add_u64 v[102:103], s[16:17], 0, v[104:105]
	v_pk_add_f32 v[100:101], v[100:101], v[100:101] op_sel:[0,1] op_sel_hi:[1,0]
	global_store_dword v[102:103], v100, off sc1
	s_waitcnt vmcnt(0)
	s_and_saveexec_b64 s[24:25], vcc
	s_cbranch_execz .LBB0_552
	s_mov_b64 s[26:27], exec
	v_mbcnt_lo_u32_b32 v99, s26, 0
	v_mbcnt_hi_u32_b32 v99, s27, v99
	v_cmp_eq_u32_e32 vcc, 0, v99
	s_and_b64 s[28:29], exec, vcc
	s_mov_b64 exec, s[28:29]
	s_cbranch_execz .LBB0_552
	s_lshl_b32 s28, s67, 6
	s_ashr_i32 s29, s28, 31
	s_lshl_b64 s[28:29], s[28:29], 2
	s_add_u32 s28, s41, s28
	s_addc_u32 s29, s42, s29
	s_bcnt1_i32_b64 s26, s[26:27]
	v_mov_b32_e32 v99, s26
	global_atomic_add v151, v99, s[28:29]

.LBB0_565:
	s_waitcnt lgkmcnt(0)
	s_barrier
	v_lshl_add_u32 v245, v194, 2, 0
	v_add_u32_e32 v245, 0x21000, v245
	ds_read2_b32 v[228:229], v245 offset1:16
	ds_read2_b32 v[230:231], v245 offset0:32 offset1:48
	ds_read2_b32 v[232:233], v245 offset0:128 offset1:144
	ds_read2_b32 v[234:235], v245 offset0:160 offset1:176
	s_waitcnt lgkmcnt(0)
	v_mov_b32_e32 v242, v195
	v_lshl_add_u32 v242, v242, 13, v156
	v_pk_mul_f32 v[140:141], v[140:141], v[228:229] op_sel_hi:[1,0]
	v_pk_mul_f32 v[142:143], v[142:143], v[228:229] op_sel_hi:[1,0]
	v_pk_mul_f32 v[140:141], v[140:141], v[212:213]
	v_pk_mul_f32 v[142:143], v[142:143], v[214:215]
	global_store_dwordx4 v242, v[140:143], s[60:61]
	v_pk_mul_f32 v[136:137], v[136:137], v[228:229] op_sel_hi:[1,0]
	v_pk_mul_f32 v[138:139], v[138:139], v[228:229] op_sel_hi:[1,0]
	v_pk_mul_f32 v[136:137], v[136:137], v[216:217]
	v_pk_mul_f32 v[138:139], v[138:139], v[218:219]
	global_store_dwordx4 v242, v[136:139], s[60:61] offset:64
	v_pk_mul_f32 v[132:133], v[132:133], v[228:229] op_sel_hi:[1,0]
	v_pk_mul_f32 v[134:135], v[134:135], v[228:229] op_sel_hi:[1,0]
	v_pk_mul_f32 v[132:133], v[132:133], v[220:221]
	v_pk_mul_f32 v[134:135], v[134:135], v[222:223]
	global_store_dwordx4 v242, v[132:135], s[60:61] offset:512
	v_pk_mul_f32 v[128:129], v[128:129], v[228:229] op_sel_hi:[1,0]
	v_pk_mul_f32 v[130:131], v[130:131], v[228:229] op_sel_hi:[1,0]
	v_pk_mul_f32 v[128:129], v[128:129], v[224:225]
	v_pk_mul_f32 v[130:131], v[130:131], v[226:227]
	global_store_dwordx4 v242, v[128:131], s[60:61] offset:576
	v_add_u32_e32 v242, 16, v195
	v_lshl_add_u32 v242, v242, 13, v156
	v_pk_mul_f32 v[124:125], v[124:125], v[228:229] op_sel:[0,1] op_sel_hi:[1,1]
	v_pk_mul_f32 v[126:127], v[126:127], v[228:229] op_sel:[0,1] op_sel_hi:[1,1]
	v_pk_mul_f32 v[124:125], v[124:125], v[212:213]
	v_pk_mul_f32 v[126:127], v[126:127], v[214:215]
	global_store_dwordx4 v242, v[124:127], s[60:61]
	v_pk_mul_f32 v[120:121], v[120:121], v[228:229] op_sel:[0,1] op_sel_hi:[1,1]
	v_pk_mul_f32 v[122:123], v[122:123], v[228:229] op_sel:[0,1] op_sel_hi:[1,1]
	v_pk_mul_f32 v[120:121], v[120:121], v[216:217]
	v_pk_mul_f32 v[122:123], v[122:123], v[218:219]
	global_store_dwordx4 v242, v[120:123], s[60:61] offset:64
	v_pk_mul_f32 v[116:117], v[116:117], v[228:229] op_sel:[0,1] op_sel_hi:[1,1]
	v_pk_mul_f32 v[118:119], v[118:119], v[228:229] op_sel:[0,1] op_sel_hi:[1,1]
	v_pk_mul_f32 v[116:117], v[116:117], v[220:221]
	v_pk_mul_f32 v[118:119], v[118:119], v[222:223]
	global_store_dwordx4 v242, v[116:119], s[60:61] offset:512
	v_pk_mul_f32 v[112:113], v[112:113], v[228:229] op_sel:[0,1] op_sel_hi:[1,1]
	v_pk_mul_f32 v[114:115], v[114:115], v[228:229] op_sel:[0,1] op_sel_hi:[1,1]
	v_pk_mul_f32 v[112:113], v[112:113], v[224:225]
	v_pk_mul_f32 v[114:115], v[114:115], v[226:227]
	global_store_dwordx4 v242, v[112:115], s[60:61] offset:576
	v_add_u32_e32 v242, 32, v195
	v_lshl_add_u32 v242, v242, 13, v156
	v_pk_mul_f32 v[92:93], v[92:93], v[230:231] op_sel_hi:[1,0]
	v_pk_mul_f32 v[94:95], v[94:95], v[230:231] op_sel_hi:[1,0]
	v_pk_mul_f32 v[92:93], v[92:93], v[212:213]
	v_pk_mul_f32 v[94:95], v[94:95], v[214:215]
	global_store_dwordx4 v242, v[92:95], s[60:61]
	v_pk_mul_f32 v[88:89], v[88:89], v[230:231] op_sel_hi:[1,0]
	v_pk_mul_f32 v[90:91], v[90:91], v[230:231] op_sel_hi:[1,0]
	v_pk_mul_f32 v[88:89], v[88:89], v[216:217]
	v_pk_mul_f32 v[90:91], v[90:91], v[218:219]
	global_store_dwordx4 v242, v[88:91], s[60:61] offset:64
	v_pk_mul_f32 v[84:85], v[84:85], v[230:231] op_sel_hi:[1,0]
	v_pk_mul_f32 v[86:87], v[86:87], v[230:231] op_sel_hi:[1,0]
	v_pk_mul_f32 v[84:85], v[84:85], v[220:221]
	v_pk_mul_f32 v[86:87], v[86:87], v[222:223]
	global_store_dwordx4 v242, v[84:87], s[60:61] offset:512
	v_pk_mul_f32 v[80:81], v[80:81], v[230:231] op_sel_hi:[1,0]
	v_pk_mul_f32 v[82:83], v[82:83], v[230:231] op_sel_hi:[1,0]
	v_pk_mul_f32 v[80:81], v[80:81], v[224:225]
	v_pk_mul_f32 v[82:83], v[82:83], v[226:227]
	global_store_dwordx4 v242, v[80:83], s[60:61] offset:576
	v_add_u32_e32 v242, 48, v195
	v_lshl_add_u32 v242, v242, 13, v156
	v_pk_mul_f32 v[76:77], v[76:77], v[230:231] op_sel:[0,1] op_sel_hi:[1,1]
	v_pk_mul_f32 v[78:79], v[78:79], v[230:231] op_sel:[0,1] op_sel_hi:[1,1]
	v_pk_mul_f32 v[76:77], v[76:77], v[212:213]
	v_pk_mul_f32 v[78:79], v[78:79], v[214:215]
	global_store_dwordx4 v242, v[76:79], s[60:61]
	v_pk_mul_f32 v[72:73], v[72:73], v[230:231] op_sel:[0,1] op_sel_hi:[1,1]
	v_pk_mul_f32 v[74:75], v[74:75], v[230:231] op_sel:[0,1] op_sel_hi:[1,1]
	v_pk_mul_f32 v[72:73], v[72:73], v[216:217]
	v_pk_mul_f32 v[74:75], v[74:75], v[218:219]
	global_store_dwordx4 v242, v[72:75], s[60:61] offset:64
	v_pk_mul_f32 v[68:69], v[68:69], v[230:231] op_sel:[0,1] op_sel_hi:[1,1]
	v_pk_mul_f32 v[70:71], v[70:71], v[230:231] op_sel:[0,1] op_sel_hi:[1,1]
	v_pk_mul_f32 v[68:69], v[68:69], v[220:221]
	v_pk_mul_f32 v[70:71], v[70:71], v[222:223]
	global_store_dwordx4 v242, v[68:71], s[60:61] offset:512
	v_pk_mul_f32 v[64:65], v[64:65], v[230:231] op_sel:[0,1] op_sel_hi:[1,1]
	v_pk_mul_f32 v[66:67], v[66:67], v[230:231] op_sel:[0,1] op_sel_hi:[1,1]
	v_pk_mul_f32 v[64:65], v[64:65], v[224:225]
	v_pk_mul_f32 v[66:67], v[66:67], v[226:227]
	global_store_dwordx4 v242, v[64:67], s[60:61] offset:576
	v_add_u32_e32 v242, 128, v195
	v_lshl_add_u32 v242, v242, 13, v156
	v_pk_mul_f32 v[60:61], v[60:61], v[232:233] op_sel_hi:[1,0]
	v_pk_mul_f32 v[62:63], v[62:63], v[232:233] op_sel_hi:[1,0]
	v_pk_mul_f32 v[60:61], v[60:61], v[212:213]
	v_pk_mul_f32 v[62:63], v[62:63], v[214:215]
	global_store_dwordx4 v242, v[60:63], s[60:61]
	v_pk_mul_f32 v[56:57], v[56:57], v[232:233] op_sel_hi:[1,0]
	v_pk_mul_f32 v[58:59], v[58:59], v[232:233] op_sel_hi:[1,0]
	v_pk_mul_f32 v[56:57], v[56:57], v[216:217]
	v_pk_mul_f32 v[58:59], v[58:59], v[218:219]
	global_store_dwordx4 v242, v[56:59], s[60:61] offset:64
	v_pk_mul_f32 v[52:53], v[52:53], v[232:233] op_sel_hi:[1,0]
	v_pk_mul_f32 v[54:55], v[54:55], v[232:233] op_sel_hi:[1,0]
	v_pk_mul_f32 v[52:53], v[52:53], v[220:221]
	v_pk_mul_f32 v[54:55], v[54:55], v[222:223]
	global_store_dwordx4 v242, v[52:55], s[60:61] offset:512
	v_pk_mul_f32 v[48:49], v[48:49], v[232:233] op_sel_hi:[1,0]
	v_pk_mul_f32 v[50:51], v[50:51], v[232:233] op_sel_hi:[1,0]
	v_pk_mul_f32 v[48:49], v[48:49], v[224:225]
	v_pk_mul_f32 v[50:51], v[50:51], v[226:227]
	global_store_dwordx4 v242, v[48:51], s[60:61] offset:576
	v_add_u32_e32 v242, 144, v195
	v_lshl_add_u32 v242, v242, 13, v156
	v_pk_mul_f32 v[44:45], v[44:45], v[232:233] op_sel:[0,1] op_sel_hi:[1,1]
	v_pk_mul_f32 v[46:47], v[46:47], v[232:233] op_sel:[0,1] op_sel_hi:[1,1]
	v_pk_mul_f32 v[44:45], v[44:45], v[212:213]
	v_pk_mul_f32 v[46:47], v[46:47], v[214:215]
	global_store_dwordx4 v242, v[44:47], s[60:61]
	v_pk_mul_f32 v[40:41], v[40:41], v[232:233] op_sel:[0,1] op_sel_hi:[1,1]
	v_pk_mul_f32 v[42:43], v[42:43], v[232:233] op_sel:[0,1] op_sel_hi:[1,1]
	v_pk_mul_f32 v[40:41], v[40:41], v[216:217]
	v_pk_mul_f32 v[42:43], v[42:43], v[218:219]
	global_store_dwordx4 v242, v[40:43], s[60:61] offset:64
	v_pk_mul_f32 v[36:37], v[36:37], v[232:233] op_sel:[0,1] op_sel_hi:[1,1]
	v_pk_mul_f32 v[38:39], v[38:39], v[232:233] op_sel:[0,1] op_sel_hi:[1,1]
	v_pk_mul_f32 v[36:37], v[36:37], v[220:221]
	v_pk_mul_f32 v[38:39], v[38:39], v[222:223]
	global_store_dwordx4 v242, v[36:39], s[60:61] offset:512
	v_pk_mul_f32 v[32:33], v[32:33], v[232:233] op_sel:[0,1] op_sel_hi:[1,1]
	v_pk_mul_f32 v[34:35], v[34:35], v[232:233] op_sel:[0,1] op_sel_hi:[1,1]
	v_pk_mul_f32 v[32:33], v[32:33], v[224:225]
	v_pk_mul_f32 v[34:35], v[34:35], v[226:227]
	global_store_dwordx4 v242, v[32:35], s[60:61] offset:576
	v_add_u32_e32 v242, 160, v195
	v_lshl_add_u32 v242, v242, 13, v156
	v_pk_mul_f32 v[28:29], v[28:29], v[234:235] op_sel_hi:[1,0]
	v_pk_mul_f32 v[30:31], v[30:31], v[234:235] op_sel_hi:[1,0]
	v_pk_mul_f32 v[28:29], v[28:29], v[212:213]
	v_pk_mul_f32 v[30:31], v[30:31], v[214:215]
	global_store_dwordx4 v242, v[28:31], s[60:61]
	v_pk_mul_f32 v[24:25], v[24:25], v[234:235] op_sel_hi:[1,0]
	v_pk_mul_f32 v[26:27], v[26:27], v[234:235] op_sel_hi:[1,0]
	v_pk_mul_f32 v[24:25], v[24:25], v[216:217]
	v_pk_mul_f32 v[26:27], v[26:27], v[218:219]
	global_store_dwordx4 v242, v[24:27], s[60:61] offset:64
	v_pk_mul_f32 v[20:21], v[20:21], v[234:235] op_sel_hi:[1,0]
	v_pk_mul_f32 v[22:23], v[22:23], v[234:235] op_sel_hi:[1,0]
	v_pk_mul_f32 v[20:21], v[20:21], v[220:221]
	v_pk_mul_f32 v[22:23], v[22:23], v[222:223]
	global_store_dwordx4 v242, v[20:23], s[60:61] offset:512
	v_pk_mul_f32 v[16:17], v[16:17], v[234:235] op_sel_hi:[1,0]
	v_pk_mul_f32 v[18:19], v[18:19], v[234:235] op_sel_hi:[1,0]
	v_pk_mul_f32 v[16:17], v[16:17], v[224:225]
	v_pk_mul_f32 v[18:19], v[18:19], v[226:227]
	global_store_dwordx4 v242, v[16:19], s[60:61] offset:576
	v_add_u32_e32 v242, 176, v195
	v_lshl_add_u32 v242, v242, 13, v156
	v_pk_mul_f32 v[12:13], v[12:13], v[234:235] op_sel:[0,1] op_sel_hi:[1,1]
	v_pk_mul_f32 v[14:15], v[14:15], v[234:235] op_sel:[0,1] op_sel_hi:[1,1]
	v_pk_mul_f32 v[12:13], v[12:13], v[212:213]
	v_pk_mul_f32 v[14:15], v[14:15], v[214:215]
	global_store_dwordx4 v242, v[12:15], s[60:61]
	v_pk_mul_f32 v[8:9], v[8:9], v[234:235] op_sel:[0,1] op_sel_hi:[1,1]
	v_pk_mul_f32 v[10:11], v[10:11], v[234:235] op_sel:[0,1] op_sel_hi:[1,1]
	v_pk_mul_f32 v[8:9], v[8:9], v[216:217]
	v_pk_mul_f32 v[10:11], v[10:11], v[218:219]
	global_store_dwordx4 v242, v[8:11], s[60:61] offset:64
	v_pk_mul_f32 v[4:5], v[4:5], v[234:235] op_sel:[0,1] op_sel_hi:[1,1]
	v_pk_mul_f32 v[6:7], v[6:7], v[234:235] op_sel:[0,1] op_sel_hi:[1,1]
	v_pk_mul_f32 v[4:5], v[4:5], v[220:221]
	v_pk_mul_f32 v[6:7], v[6:7], v[222:223]
	global_store_dwordx4 v242, v[4:7], s[60:61] offset:512
	v_pk_mul_f32 v[0:1], v[0:1], v[234:235] op_sel:[0,1] op_sel_hi:[1,1]
	v_pk_mul_f32 v[2:3], v[2:3], v[234:235] op_sel:[0,1] op_sel_hi:[1,1]
	v_pk_mul_f32 v[0:1], v[0:1], v[224:225]
	v_pk_mul_f32 v[2:3], v[2:3], v[226:227]
	global_store_dwordx4 v242, v[0:3], s[60:61] offset:576
	s_mov_b64 s[2:3], -1
	s_cmp_eq_u32 s66, 3
	s_cbranch_scc1 .LBB0_527
	s_andn2_b64 vcc, exec, s[8:9]
	s_cbranch_vccnz .LBB0_526
	s_barrier
	s_branch .LBB0_526
